# v36 + static s_setprio 1 for waves 4-7 across the attention phase (DSA + band), reset at phase end
# speedup vs baseline: 1.0005x; 1.0005x over previous
; #define LAS __attribute__((address_space(3)))
; #define OTID() ({ int t_ = threadIdx.x; asm volatile("" : "+v"(t_)); t_; })
; #define LANE() (OTID() & 63)
; __global__ void __launch_bounds__(NWAVES * 64, 2) mega(Args a) {
;     ...
;         if (IN(pb + 4)) for (int rep_ = 0; rep_ < ATT_REPS; ++rep_) {
;     ...
;             for (int dr_ = 0; dr_ < DSA_REPS; ++dr_) for (int idx = vcu; idx < NB_ * 128; idx += G) { const int k = idx >> 8, v = idx & 255, b = (v >> 5) + 8 * (k & 1), c32 = v & 31, k2 = k >> 1, blk = 32 * k2 + ((k2 & 1) ? 31 - c32 : c32);
;                 dsa_unit(b, blk, p.BIG, p.OB, lds, wave, OTID()); }
;     ...
;             LAS unsigned char* vl = lds + C_VST + wave * 4096;
;             for (int br_ = 0; br_ < BAND_REPS; ++br_) for (int u = gw; u < 4 * NB_ * 8 * (SEQ_ / (16 * BAND_NQ)); u += ngw) band_unit<BAND_NQ>(u, p.BIG, p.OB, p.ACX, p.LSE, p.sink + l * 8, vl, LANE());
.LBB0_577:
	s_andn2_b64 vcc, exec, s[4:5]
	s_cbranch_vccnz .LBB0_1351
	v_readfirstlane_b32 s0, v227
	s_cmpk_lt_u32 s0, 0x100
	s_cbranch_scc1 .Lmy_prio_skip
	s_setprio 1
.Lmy_prio_skip:
	v_readlane_b32 s0, v252, 17
	v_readlane_b32 s1, v252, 18
	v_writelane_b32 v255, s22, 27
	s_andn2_b64 vcc, exec, s[0:1]
	v_readlane_b32 s1, v250, 2
	v_writelane_b32 v255, s23, 28
	s_cbranch_vccz .LBB0_582

; #define SEAM(k) do { } while (0)
; #define SEAM(k) do { if (IN(k) && IN((k) + 1)) { if ((k) == 0) grid.sync(); else xcd_barrier(xbar); } } while (0)
; __device__ __forceinline__ void xcd_barrier(const XcdBarrier& b) {
;     asm volatile("s_waitcnt vmcnt(0)" ::: "memory");
;     __syncthreads();
;     if (threadIdx.x == 0) {
;         unsigned* bar = b.bar;
;         __builtin_amdgcn_s_waitcnt(0);
;         unsigned nloc = b.st[0], nx = b.st[1];
;         if (nloc == 0u) { xcd_barrier_complete(bar, b.x, nloc, nx); b.st[0] = nloc; b.st[1] = nx; }
; __global__ void __launch_bounds__(NWAVES * 64, 2) mega(Args a) {
;     ...
;         }
;         SEAM(pb + 4);
.LBB0_1297:
	s_setprio 0
	v_readlane_b32 s0, v255, 20
	v_readlane_b32 s2, v255, 12
	s_add_i32 s0, s0, 5
	v_readlane_b32 s3, v255, 13
	s_cmp_lt_i32 s0, s3
	s_cbranch_scc0 .LBB0_1351
	s_waitcnt vmcnt(0)
	s_waitcnt lgkmcnt(0)
	s_barrier
	s_mov_b64 s[4:5], exec
	v_readlane_b32 s2, v250, 29
	v_readlane_b32 s3, v250, 30
	s_and_b64 s[2:3], s[4:5], s[2:3]
	s_mov_b64 exec, s[2:3]
	s_cbranch_execz .LBB0_1350
	v_readlane_b32 s1, v255, 10
	s_waitcnt vmcnt(0) expcnt(0) lgkmcnt(0)
	s_nop 0
	v_mov_b32_e32 v0, s1
	ds_read_b32 v3, v0
	v_readlane_b32 s1, v255, 11
	s_waitcnt lgkmcnt(0)
	v_cmp_ne_u32_e32 vcc, 0, v3
	v_mov_b32_e32 v0, s1
	ds_read_b32 v2, v0
	s_cbranch_vccnz .LBB0_1314
	s_mov_b32 s2, 1
	s_branch .LBB0_1302
